# v87 + ssd_s3 waves 4..7 take row tiles 7..4 (the two waves of a SIMD get a balanced number of causal y_diag blocks)
# baseline (speedup 1.0000x reference)
; __device__ __forceinline__ void ssd_cumsum(const Params& p, int row0, int g, float* csb, float* dtb) {
;     const int tid = threadIdx.x, hh = tid >> 7, l = tid & 127, h = g * 4 + hh, lane = tid & 63;
;     const float dt = ((const float*)(p.ws + WS_DT))[(size_t)(row0 + l) * 16 + h];
;     const float a = -__expf(p.a_log[h]);
;     float v = dt * a;
; #pragma unroll
;     for (int off = 1; off < 64; off <<= 1) { const float t = __shfl_up(v, off); if (lane >= off) v += t; }
;     dtb[tid] = dt; csb[tid] = v;
;     __syncthreads();
;     if (l >= 64) { v += csb[hh * 128 + 63]; }
;     __syncthreads();
;     csb[tid] = v;
;     __syncthreads();
; }
; __device__ __forceinline__ void ssd_s3_unit(const Params& p, int unit, unsigned char* ldsb) {
;     const int g = unit & 3, c = (unit >> 2) & 31, b = unit >> 7;
;     const int tid = threadIdx.x, lane = tid & 63, wave = __builtin_amdgcn_readfirstlane(tid >> 6), l15 = lane & 15, quad = lane >> 4;
;     bfu* Cs = (bfu*)ldsb;
;     bfu* Bs = Cs + 128 * 136;
;     bfu* XT4 = Bs + 128 * 136;
;     float* csb = (float*)(XT4 + 256 * 136);
;     float* dtb = csb + 512;
;     const int row0 = b * 4096 + c * 128;
;     const bfu* xbc = (const bfu*)(p.ws + WS_XBC);
;     const bfu* proj = (const bfu*)(p.ws + WS_PROJ);
;     ssd_cumsum(p, row0, g, csb, dtb);
; #pragma unroll
;     for (int i = 0; i < 4; ++i) {
;         const int e = tid + 512 * i, l = e >> 4, n8 = (e & 15) * 8;
;         *(uint4*)(Bs + l * 136 + n8) = *(const uint4*)(xbc + (size_t)(row0 + l) * 2048 + 1024 + g * 128 + n8);
;         *(uint4*)(Cs + l * 136 + n8) = *(const uint4*)(xbc + (size_t)(row0 + l) * 2048 + 1536 + g * 128 + n8);
;     }
; #pragma unroll
;     for (int i = 0; i < 8; ++i) {
;         const int e = tid + 512 * i, l = e & 127, p8 = (e >> 7) * 8;
;         const uint4 v = *(const uint4*)(xbc + (size_t)(row0 + l) * 2048 + g * 256 + p8);
;         bfu* tp = XT4 + p8 * 136 + l;
;         tp[0] = (bfu)(v.x & 0xffff); tp[136] = (bfu)(v.x >> 16); tp[2 * 136] = (bfu)(v.y & 0xffff); tp[3 * 136] = (bfu)(v.y >> 16);
;         tp[4 * 136] = (bfu)(v.z & 0xffff); tp[5 * 136] = (bfu)(v.z >> 16); tp[6 * 136] = (bfu)(v.w & 0xffff); tp[7 * 136] = (bfu)(v.w >> 16);
;     }
.LBB0_525:
	v_readlane_b32 s90, v252, 1
	v_readlane_b32 s91, v252, 2
	s_ashr_i32 s6, s87, 7
	s_lshl_b32 s0, s87, 5
	s_lshl_b32 s7, s6, 12
	s_and_b32 s0, s0, 0xf80
	s_or_b32 s21, s0, s7
	s_load_dwordx2 s[88:89], s[90:91], 0xb8
	s_load_dwordx2 s[0:1], s[90:91], 0x50
	s_and_b32 s20, s87, 3
	s_lshl_b32 s8, s20, 2
	v_or_b32_e32 v0, s21, v113
	v_ashrrev_i32_e32 v1, 31, v0
	v_add_lshl_u32 v52, s8, v196, 2
	v_lshlrev_b64 v[2:3], 6, v[0:1]
	s_waitcnt lgkmcnt(0)
	global_load_dword v4, v52, s[0:1]
	v_lshl_add_u64 v[2:3], s[88:89], 0, v[2:3]
	v_lshl_add_u64 v[2:3], v[2:3], 0, v[52:53]
	s_mov_b32 s0, 0x16600000
	v_add_co_u32_e32 v2, vcc, s0, v2
	v_add_u32_e32 v5, -1, v155
	s_nop 0
	v_addc_co_u32_e32 v3, vcc, 0, v3, vcc
	global_load_dword v2, v[2:3], off
	s_add_u32 s10, s88, 0x16800000
	s_addc_u32 s11, s89, 0
	s_lshl_b32 s12, s20, 8
	s_lshl_b32 s14, s20, 9
	v_or_b32_e32 v182, s21, v112
	v_lshlrev_b32_e32 v182, 12, v182
	v_add3_u32 v182, v182, s12, v84
	v_mov_b32_e32 v183, 0
	v_lshl_add_u64 v[182:183], s[10:11], 0, v[182:183]
	global_load_dwordx4 v[182:185], v[182:183], off offset:2048
	v_or_b32_e32 v186, s21, v112
	v_lshlrev_b32_e32 v186, 12, v186
	v_add3_u32 v186, v186, s12, v84
	v_mov_b32_e32 v187, 0
	v_lshl_add_u64 v[186:187], s[10:11], 0, v[186:187]
	global_load_dwordx4 v[186:189], v[186:187], off offset:3072
	v_or_b32_e32 v190, s21, v118
	v_lshlrev_b32_e32 v190, 12, v190
	v_add3_u32 v190, v190, s12, v84
	v_mov_b32_e32 v191, 0
	v_lshl_add_u64 v[190:191], s[10:11], 0, v[190:191]
	global_load_dwordx4 v[190:193], v[190:191], off offset:2048
	v_or_b32_e32 v198, s21, v118
	v_lshlrev_b32_e32 v198, 12, v198
	v_add3_u32 v198, v198, s12, v84
	v_mov_b32_e32 v199, 0
	v_lshl_add_u64 v[198:199], s[10:11], 0, v[198:199]
	global_load_dwordx4 v[198:201], v[198:199], off offset:3072
	v_or_b32_e32 v202, 64, v112
	v_or_b32_e32 v202, s21, v202
	v_lshlrev_b32_e32 v202, 12, v202
	v_add3_u32 v202, v202, s12, v84
	v_mov_b32_e32 v203, 0
	v_lshl_add_u64 v[202:203], s[10:11], 0, v[202:203]
	global_load_dwordx4 v[202:205], v[202:203], off offset:2048
	v_or_b32_e32 v206, 64, v112
	v_or_b32_e32 v206, s21, v206
	v_lshlrev_b32_e32 v206, 12, v206
	v_add3_u32 v206, v206, s12, v84
	v_mov_b32_e32 v207, 0
	v_lshl_add_u64 v[206:207], s[10:11], 0, v[206:207]
	global_load_dwordx4 v[206:209], v[206:207], off offset:3072
	v_add_u32_e32 v210, s21, v120
	v_lshlrev_b32_e32 v210, 12, v210
	v_add3_u32 v210, v210, s12, v84
	v_mov_b32_e32 v211, 0
	v_lshl_add_u64 v[210:211], s[10:11], 0, v[210:211]
	global_load_dwordx4 v[210:213], v[210:211], off offset:2048
	v_add_u32_e32 v214, s21, v120
	v_lshlrev_b32_e32 v214, 12, v214
	v_add3_u32 v214, v214, s12, v84
	v_mov_b32_e32 v215, 0
	v_lshl_add_u64 v[214:215], s[10:11], 0, v[214:215]
	global_load_dwordx4 v[214:217], v[214:215], off offset:3072
	v_or_b32_e32 v218, s21, v113
	v_lshlrev_b32_e32 v218, 12, v218
	v_add3_u32 v218, v218, s14, v86
	v_mov_b32_e32 v219, 0
	v_lshl_add_u64 v[218:219], s[10:11], 0, v[218:219]
	global_load_dwordx4 v[218:221], v[218:219], off
	v_or_b32_e32 v222, s21, v113
	v_lshlrev_b32_e32 v222, 12, v222
	v_add3_u32 v222, v222, s14, v88
	v_mov_b32_e32 v223, 0
	v_lshl_add_u64 v[222:223], s[10:11], 0, v[222:223]
	global_load_dwordx4 v[222:225], v[222:223], off
	v_or_b32_e32 v226, s21, v113
	v_lshlrev_b32_e32 v226, 12, v226
	v_add3_u32 v226, v226, s14, v90
	v_mov_b32_e32 v227, 0
	v_lshl_add_u64 v[226:227], s[10:11], 0, v[226:227]
	global_load_dwordx4 v[226:229], v[226:227], off
	v_or_b32_e32 v230, s21, v113
	v_lshlrev_b32_e32 v230, 12, v230
	v_add3_u32 v230, v230, s14, v92
	v_mov_b32_e32 v231, 0
	v_lshl_add_u64 v[230:231], s[10:11], 0, v[230:231]
	global_load_dwordx4 v[230:233], v[230:231], off
	v_or_b32_e32 v234, s21, v113
	v_lshlrev_b32_e32 v234, 12, v234
	v_add3_u32 v234, v234, s14, v86
	v_mov_b32_e32 v235, 0
	v_lshl_add_u64 v[234:235], s[10:11], 0, v[234:235]
	global_load_dwordx4 v[234:237], v[234:235], off offset:256
	v_or_b32_e32 v238, s21, v113
	v_lshlrev_b32_e32 v238, 12, v238
	v_add3_u32 v238, v238, s14, v94
	v_mov_b32_e32 v239, 0
	v_lshl_add_u64 v[238:239], s[10:11], 0, v[238:239]
	global_load_dwordx4 v[238:241], v[238:239], off
	v_or_b32_e32 v242, s21, v113
	v_lshlrev_b32_e32 v242, 12, v242
	v_add3_u32 v242, v242, s14, v86
	v_mov_b32_e32 v243, 0
	v_lshl_add_u64 v[242:243], s[10:11], 0, v[242:243]
	global_load_dwordx4 v[242:245], v[242:243], off offset:384
	v_or_b32_e32 v246, s21, v113
	v_lshlrev_b32_e32 v246, 12, v246
	v_add3_u32 v246, v246, s14, v96
	v_mov_b32_e32 v247, 0
	v_lshl_add_u64 v[246:247], s[10:11], 0, v[246:247]
	global_load_dwordx4 v[246:249], v[246:247], off
	v_and_b32_e32 v3, 64, v155
	v_cmp_lt_i32_e32 vcc, v5, v3
	v_add_u32_e32 v7, -2, v155
	v_readlane_b32 s0, v252, 12
	v_cndmask_b32_e32 v5, v5, v155, vcc
	v_lshlrev_b32_e32 v5, 2, v5
	v_cmp_lt_i32_e32 vcc, v7, v3
	v_readlane_b32 s1, v252, 13
	s_waitcnt vmcnt(17)
	v_mul_f32_e32 v4, 0x3fb8aa3b, v4
	v_exp_f32_e32 v4, v4
	v_cndmask_b32_e32 v7, v7, v155, vcc
	v_lshlrev_b32_e32 v7, 2, v7
	s_waitcnt vmcnt(16)
	v_mul_f32_e64 v6, v2, -v4
	ds_bpermute_b32 v5, v5, v6
	ds_write_b32 v114, v2
	s_waitcnt lgkmcnt(1)
	v_fma_f32 v4, v2, -v4, v5
	v_cndmask_b32_e64 v4, v4, v6, s[0:1]
	ds_bpermute_b32 v5, v7, v4
	v_add_u32_e32 v6, -4, v155
	v_cmp_lt_i32_e32 vcc, v6, v3
	v_readlane_b32 s0, v252, 14
	v_readlane_b32 s1, v252, 15
	v_cndmask_b32_e32 v6, v6, v155, vcc
	s_waitcnt lgkmcnt(0)
	v_add_f32_e32 v5, v4, v5
	v_lshlrev_b32_e32 v6, 2, v6
	v_cndmask_b32_e64 v4, v5, v4, s[0:1]
	ds_bpermute_b32 v5, v6, v4
	v_add_u32_e32 v6, -8, v155
	v_cmp_lt_i32_e32 vcc, v6, v3
	v_readlane_b32 s0, v252, 16
	v_readlane_b32 s1, v252, 17
	v_cndmask_b32_e32 v6, v6, v155, vcc
	s_waitcnt lgkmcnt(0)
	v_add_f32_e32 v5, v4, v5
	v_lshlrev_b32_e32 v6, 2, v6
	v_cndmask_b32_e64 v4, v5, v4, s[0:1]
	ds_bpermute_b32 v5, v6, v4
	v_add_u32_e32 v6, -16, v155
	v_cmp_lt_i32_e32 vcc, v6, v3
	v_readlane_b32 s0, v252, 18
	v_readlane_b32 s1, v252, 19
	v_cndmask_b32_e32 v6, v6, v155, vcc
	s_waitcnt lgkmcnt(0)
	v_add_f32_e32 v5, v4, v5
	v_lshlrev_b32_e32 v6, 2, v6
	v_cndmask_b32_e64 v4, v5, v4, s[0:1]
	ds_bpermute_b32 v5, v6, v4
	v_subrev_u32_e32 v6, 32, v155
	v_cmp_lt_i32_e32 vcc, v6, v3
	v_readlane_b32 s0, v252, 20
	v_readlane_b32 s1, v252, 21
	v_cndmask_b32_e32 v3, v6, v155, vcc
	s_waitcnt lgkmcnt(0)
	v_add_f32_e32 v5, v4, v5
	v_lshlrev_b32_e32 v3, 2, v3
	v_cndmask_b32_e64 v4, v5, v4, s[0:1]
	ds_bpermute_b32 v3, v3, v4
	v_readfirstlane_b32 vcc_lo, v172
	s_nop 0
	s_sub_u32 s32, 0x2c0, vcc_lo
	s_cmp_lt_u32 vcc_lo, 0x100
	s_cselect_b32 vcc_lo, vcc_lo, s32
	s_waitcnt lgkmcnt(0)
	v_add_f32_e32 v2, v4, v3
	v_cndmask_b32_e64 v2, v2, v4, s[16:17]
	ds_write_b32 v115, v2
	s_waitcnt lgkmcnt(0)
	s_barrier
	s_and_saveexec_b64 s[0:1], s[18:19]
	s_cbranch_execz .LBB0_527
	ds_read_b32 v3, v116 offset:252
	s_waitcnt lgkmcnt(0)
	v_add_f32_e32 v2, v2, v3
